# waves 4-7: P.V section at s_setprio 2, their init+QK^T back at 1 (softmax 0); rest as v008
# speedup vs baseline: 1.0135x; 1.0046x over previous
; #define SBAR() __builtin_amdgcn_sched_barrier(0)
; #define PV_LOAD(S, DD) do { S[0] = tr_read<v_off8(DD, 0, 0)>(vb); S[1] = tr_read<v_off8(DD, 0, 1)>(vb); S[2] = tr_read<v_off8(DD, 1, 0)>(vb); S[3] = tr_read<v_off8(DD, 1, 1)>(vb); \
;     S[4] = tr_read<v_off8(DD, 2, 0)>(vb); S[5] = tr_read<v_off8(DD, 2, 1)>(vb); S[6] = tr_read<v_off8(DD, 3, 0)>(vb); S[7] = tr_read<v_off8(DD, 3, 1)>(vb); } while (0)
; #define PV_MMA(OD, S) do { OD = __builtin_amdgcn_mfma_f32_32x32x16_bf16(pa0, PV_PK(S[0], S[1]), OD, 0, 0, 0); OD = __builtin_amdgcn_mfma_f32_32x32x16_bf16(pa1, PV_PK(S[2], S[3]), OD, 0, 0, 0); \
;     OD = __builtin_amdgcn_mfma_f32_32x32x16_bf16(pa2, PV_PK(S[4], S[5]), OD, 0, 0, 0); OD = __builtin_amdgcn_mfma_f32_32x32x16_bf16(pa3, PV_PK(S[6], S[7]), OD, 0, 0, 0); } while (0)
; #define PV_W8() do { asm volatile("s_waitcnt lgkmcnt(8)" ::: "memory"); SBAR(); } while (0)
; #define PV_W0() do { asm volatile("s_waitcnt lgkmcnt(0)" ::: "memory"); SBAR(); } while (0)
; __device__ __forceinline__ void pv8(f32x16* o, int vb, bf16x8 pa0, bf16x8 pa1, bf16x8 pa2, bf16x8 pa3) {
;   s16x4 A[8], B[8];
;   PV_LOAD(A, 0);
;   PV_LOAD(B, 1); PV_W8(); PV_MMA(o[0], A); SBAR();
;   PV_LOAD(A, 2); PV_W8(); PV_MMA(o[1], B); SBAR();
;   PV_LOAD(B, 3); PV_W8(); PV_MMA(o[2], A); SBAR();
;   PV_LOAD(A, 4); PV_W8(); PV_MMA(o[3], B); SBAR();
;   PV_LOAD(B, 5); PV_W8(); PV_MMA(o[4], A); SBAR();
;   PV_LOAD(A, 6); PV_W8(); PV_MMA(o[5], B); SBAR();
;   PV_LOAD(B, 7); PV_W8(); PV_MMA(o[6], A); SBAR();
;   PV_W0(); PV_MMA(o[7], B);
; }
; __device__ __forceinline__ void attn_pass(const bf16_t* __restrict__ Qb, const bf16_t* __restrict__ Kh, const bf16_t* __restrict__ Vh,
;                                           float* Ob, int mode, float lam, int qpos0, int seq, char* lds, const int wv, bf16_t* OBh) {
;     ...
;       __builtin_amdgcn_s_setprio(1);
;       pv8(o, vb0 + bprev, pa0, pa1, pa2, pa3);
;       SBAR();
;       { const int k0 = j * KVBLK; qkt(p0, p1, lds + bcur, qr, r32, hi, tab, k0 - qlane, FARMODE(k0)); }
;       __builtin_amdgcn_s_setprio(0);
.LBB0_113:
	s_setprio 2
	v_add_u32_e32 v160, s8, v226
	ds_read_b64_tr_b16 v[144:145], v160 offset:0
	ds_read_b64_tr_b16 v[146:147], v160 offset:0x800
	ds_read_b64_tr_b16 v[148:149], v160 offset:0x1000
	ds_read_b64_tr_b16 v[150:151], v160 offset:0x1800
	ds_read_b64_tr_b16 v[152:153], v160 offset:0x2000
	ds_read_b64_tr_b16 v[154:155], v160 offset:0x2800
	ds_read_b64_tr_b16 v[156:157], v160 offset:0x3000
	ds_read_b64_tr_b16 v[158:159], v160 offset:0x3800
	ds_read_b64_tr_b16 v[194:195], v160 offset:0x200
	ds_read_b64_tr_b16 v[196:197], v160 offset:0xa00
	ds_read_b64_tr_b16 v[198:199], v160 offset:0x1200
	ds_read_b64_tr_b16 v[200:201], v160 offset:0x1a00
	ds_read_b64_tr_b16 v[202:203], v160 offset:0x2200
	ds_read_b64_tr_b16 v[204:205], v160 offset:0x2a00
	ds_read_b64_tr_b16 v[206:207], v160 offset:0x3200
	ds_read_b64_tr_b16 v[208:209], v160 offset:0x3a00
	s_waitcnt lgkmcnt(8)
	s_nop 0
	v_mfma_f32_32x32x16_bf16 v[96:111], v[128:131], v[144:147], v[96:111]
	v_mfma_f32_32x32x16_bf16 v[96:111], v[132:135], v[148:151], v[96:111]
	v_mfma_f32_32x32x16_bf16 v[96:111], v[136:139], v[152:155], v[96:111]
	v_mfma_f32_32x32x16_bf16 v[96:111], v[140:143], v[156:159], v[96:111]
	ds_read_b64_tr_b16 v[144:145], v160 offset:0x400
	ds_read_b64_tr_b16 v[146:147], v160 offset:0xc00
	ds_read_b64_tr_b16 v[148:149], v160 offset:0x1400
	ds_read_b64_tr_b16 v[150:151], v160 offset:0x1c00
	ds_read_b64_tr_b16 v[152:153], v160 offset:0x2400
	ds_read_b64_tr_b16 v[154:155], v160 offset:0x2c00
	ds_read_b64_tr_b16 v[156:157], v160 offset:0x3400
	ds_read_b64_tr_b16 v[158:159], v160 offset:0x3c00
	s_waitcnt lgkmcnt(8)
	v_mfma_f32_32x32x16_bf16 v[112:127], v[128:131], v[194:197], v[112:127]
	v_mfma_f32_32x32x16_bf16 v[112:127], v[132:135], v[198:201], v[112:127]
	v_mfma_f32_32x32x16_bf16 v[112:127], v[136:139], v[202:205], v[112:127]
	v_mfma_f32_32x32x16_bf16 v[112:127], v[140:143], v[206:209], v[112:127]
	ds_read_b64_tr_b16 v[194:195], v160 offset:0x600
	ds_read_b64_tr_b16 v[196:197], v160 offset:0xe00
	ds_read_b64_tr_b16 v[198:199], v160 offset:0x1600
	ds_read_b64_tr_b16 v[200:201], v160 offset:0x1e00
	ds_read_b64_tr_b16 v[202:203], v160 offset:0x2600
	ds_read_b64_tr_b16 v[204:205], v160 offset:0x2e00
	ds_read_b64_tr_b16 v[206:207], v160 offset:0x3600
	ds_read_b64_tr_b16 v[208:209], v160 offset:0x3e00
	s_waitcnt lgkmcnt(8)
	v_mfma_f32_32x32x16_bf16 v[80:95], v[128:131], v[144:147], v[80:95]
	v_mfma_f32_32x32x16_bf16 v[80:95], v[132:135], v[148:151], v[80:95]
	v_mfma_f32_32x32x16_bf16 v[80:95], v[136:139], v[152:155], v[80:95]
	v_mfma_f32_32x32x16_bf16 v[80:95], v[140:143], v[156:159], v[80:95]
	ds_read_b64_tr_b16 v[144:145], v160 offset:0x4000
	ds_read_b64_tr_b16 v[146:147], v160 offset:0x4800
	ds_read_b64_tr_b16 v[148:149], v160 offset:0x5000
	ds_read_b64_tr_b16 v[150:151], v160 offset:0x5800
	ds_read_b64_tr_b16 v[152:153], v160 offset:0x6000
	ds_read_b64_tr_b16 v[154:155], v160 offset:0x6800
	ds_read_b64_tr_b16 v[156:157], v160 offset:0x7000
	ds_read_b64_tr_b16 v[158:159], v160 offset:0x7800
	s_waitcnt lgkmcnt(8)
	v_mfma_f32_32x32x16_bf16 v[64:79], v[128:131], v[194:197], v[64:79]
	v_mfma_f32_32x32x16_bf16 v[64:79], v[132:135], v[198:201], v[64:79]
	v_mfma_f32_32x32x16_bf16 v[64:79], v[136:139], v[202:205], v[64:79]
	v_mfma_f32_32x32x16_bf16 v[64:79], v[140:143], v[206:209], v[64:79]
	ds_read_b64_tr_b16 v[194:195], v160 offset:0x4200
	ds_read_b64_tr_b16 v[196:197], v160 offset:0x4a00
	ds_read_b64_tr_b16 v[198:199], v160 offset:0x5200
	ds_read_b64_tr_b16 v[200:201], v160 offset:0x5a00
	ds_read_b64_tr_b16 v[202:203], v160 offset:0x6200
	ds_read_b64_tr_b16 v[204:205], v160 offset:0x6a00
	ds_read_b64_tr_b16 v[206:207], v160 offset:0x7200
	ds_read_b64_tr_b16 v[208:209], v160 offset:0x7a00
	s_waitcnt lgkmcnt(8)
	v_mfma_f32_32x32x16_bf16 v[48:63], v[128:131], v[144:147], v[48:63]
	v_mfma_f32_32x32x16_bf16 v[48:63], v[132:135], v[148:151], v[48:63]
	v_mfma_f32_32x32x16_bf16 v[48:63], v[136:139], v[152:155], v[48:63]
	v_mfma_f32_32x32x16_bf16 v[48:63], v[140:143], v[156:159], v[48:63]
	ds_read_b64_tr_b16 v[144:145], v160 offset:0x4400
	ds_read_b64_tr_b16 v[146:147], v160 offset:0x4c00
	ds_read_b64_tr_b16 v[148:149], v160 offset:0x5400
	ds_read_b64_tr_b16 v[150:151], v160 offset:0x5c00
	ds_read_b64_tr_b16 v[152:153], v160 offset:0x6400
	ds_read_b64_tr_b16 v[154:155], v160 offset:0x6c00
	ds_read_b64_tr_b16 v[156:157], v160 offset:0x7400
	ds_read_b64_tr_b16 v[158:159], v160 offset:0x7c00
	s_waitcnt lgkmcnt(8)
	v_mfma_f32_32x32x16_bf16 v[32:47], v[128:131], v[194:197], v[32:47]
	v_mfma_f32_32x32x16_bf16 v[32:47], v[132:135], v[198:201], v[32:47]
	v_mfma_f32_32x32x16_bf16 v[32:47], v[136:139], v[202:205], v[32:47]
	v_mfma_f32_32x32x16_bf16 v[32:47], v[140:143], v[206:209], v[32:47]
	ds_read_b64_tr_b16 v[194:195], v160 offset:0x4600
	ds_read_b64_tr_b16 v[196:197], v160 offset:0x4e00
	ds_read_b64_tr_b16 v[198:199], v160 offset:0x5600
	ds_read_b64_tr_b16 v[200:201], v160 offset:0x5e00
	ds_read_b64_tr_b16 v[202:203], v160 offset:0x6600
	ds_read_b64_tr_b16 v[204:205], v160 offset:0x6e00
	ds_read_b64_tr_b16 v[206:207], v160 offset:0x7600
	ds_read_b64_tr_b16 v[208:209], v160 offset:0x7e00
	s_waitcnt lgkmcnt(8)
	v_mfma_f32_32x32x16_bf16 v[16:31], v[128:131], v[144:147], v[16:31]
	v_mfma_f32_32x32x16_bf16 v[16:31], v[132:135], v[148:151], v[16:31]
	v_mfma_f32_32x32x16_bf16 v[16:31], v[136:139], v[152:155], v[16:31]
	v_mfma_f32_32x32x16_bf16 v[16:31], v[140:143], v[156:159], v[16:31]
	s_waitcnt lgkmcnt(0)
	v_mfma_f32_32x32x16_bf16 v[0:15], v[128:131], v[194:197], v[0:15]
	v_mfma_f32_32x32x16_bf16 v[0:15], v[132:135], v[198:201], v[0:15]
	v_mfma_f32_32x32x16_bf16 v[0:15], v[136:139], v[202:205], v[0:15]
	v_mfma_f32_32x32x16_bf16 v[0:15], v[140:143], v[206:209], v[0:15]
	s_setprio 1
	s_cmpk_lt_u32 s77, 0x113
	s_cbranch_scc1 .LBB0_115
	s_add_i32 s8, s77, 0xffffff67
	s_cmpk_gt_i32 s8, 0xff66
	s_cselect_b32 s8, 0x600, 0
	s_add_i32 s8, s8, 0
	s_add_i32 s8, s8, 0x24800
	v_mov_b32_e32 v128, s8
	ds_read_b32 v160, v128
	s_mov_b64 s[8:9], 0
	s_waitcnt lgkmcnt(0)
	v_mov_b64_e32 v[144:145], v[160:161]
	v_mov_b64_e32 v[146:147], v[162:163]
	v_mov_b64_e32 v[148:149], v[164:165]
	v_mov_b64_e32 v[150:151], v[166:167]
	v_mov_b64_e32 v[152:153], v[168:169]
	v_mov_b64_e32 v[154:155], v[170:171]
	v_mov_b64_e32 v[156:157], v[172:173]
	v_mov_b64_e32 v[158:159], v[174:175]
	s_branch .LBB0_116
